# P5 step 3: per-block init reads issued as one batch; first 7 diagonal coefficients read at block top, other 8 right before the chain
# baseline (speedup 1.0000x reference)
; __device__ __forceinline__ float bf2f(unsigned short b) { return __uint_as_float((unsigned)b << 16); }
; __device__ __forceinline__ void prep_unit(const int PREP_STEPS, LAS unsigned char* lds, int uidx, bf16* Qg, bf16* Kg, bf16* Vg, bf16* KT, bf16* QK, const bf16* HALO, const float* wconv, const float* BETA, const float* GG, float* GC) {
;     ...
;             float au[16], aw[16];
; #pragma unroll
;             for (int r = 0; r < 16; ++r) { au[r] = bf2f(Vs[(16 * I + r) * 136 + c]) * betas[16 * I + r]; aw[r] = bf2f(Ks[(16 * I + r) * 136 + c]) * egcs[16 * I + r]; }
;             const int l16 = lane & 15;
; #pragma unroll 2
;             for (int j = 0; j < 16 * I; ++j) {
;                 const float xu = bf2f(Vs[j * 136 + c]), xw = bf2f(Ks[j * 136 + c]);
;                 const int av = __builtin_bit_cast(int, Af[j * 68 + 16 * I + l16]);
;                 Rows16<0>::run(av, xu, xw, au, aw, -1);
;             }
; #pragma unroll
;             for (int q = 0; q < 15; ++q) {
;                 const float xu = au[q], xw = aw[q];
;                 const int av = __builtin_bit_cast(int, Af[(16 * I + q) * 68 + 16 * I + l16]);
.Lfs_I:
	s_mul_i32 s0, s1, 0x1140
	v_add_u32_e32 v198, s0, v145
	ds_read_b32 v20, v198
	ds_read_b32 v21, v198 offset:272
	ds_read_b32 v22, v198 offset:544
	ds_read_b32 v23, v198 offset:816
	ds_read_b32 v24, v198 offset:1088
	ds_read_b32 v25, v198 offset:1360
	ds_read_b32 v26, v198 offset:1632
	ds_read_b128 v[40:43], v48
	ds_read_b128 v[44:47], v48 offset:16
	ds_read_u16 v28, v17
	ds_read_u16 v29, v17 offset:272
	ds_read_u16 v30, v17 offset:544
	ds_read_u16 v31, v17 offset:816
	ds_read_u16 v32, v17 offset:1088
	ds_read_u16 v33, v17 offset:1360
	ds_read_u16 v34, v17 offset:1632
	ds_read_u16 v35, v17 offset:1904
	ds_read_b128 v[168:171], v48 offset:32
	ds_read_b128 v[172:175], v48 offset:48
	ds_read_u16 v176, v17 offset:2176
	ds_read_u16 v177, v17 offset:2448
	ds_read_u16 v178, v17 offset:2720
	ds_read_u16 v179, v17 offset:2992
	ds_read_u16 v180, v17 offset:3264
	ds_read_u16 v181, v17 offset:3536
	ds_read_u16 v182, v17 offset:3808
	ds_read_u16 v183, v17 offset:4080
	s_waitcnt lgkmcnt(0)
	v_lshlrev_b32_e32 v28, 16, v28
	v_lshlrev_b32_e32 v29, 16, v29
	v_lshlrev_b32_e32 v30, 16, v30
	v_lshlrev_b32_e32 v31, 16, v31
	v_lshlrev_b32_e32 v32, 16, v32
	v_lshlrev_b32_e32 v33, 16, v33
	v_lshlrev_b32_e32 v34, 16, v34
	v_lshlrev_b32_e32 v35, 16, v35
	v_lshlrev_b32_e32 v176, 16, v176
	v_lshlrev_b32_e32 v177, 16, v177
	v_lshlrev_b32_e32 v178, 16, v178
	v_lshlrev_b32_e32 v179, 16, v179
	v_lshlrev_b32_e32 v180, 16, v180
	v_lshlrev_b32_e32 v181, 16, v181
	v_lshlrev_b32_e32 v182, 16, v182
	v_lshlrev_b32_e32 v183, 16, v183
	v_mul_f32_e32 v0, v28, v40
	v_mul_f32_e32 v4, v29, v41
	v_mul_f32_e32 v8, v30, v42
	v_mul_f32_e32 v12, v31, v43
	v_mul_f32_e32 v1, v32, v44
	v_mul_f32_e32 v5, v33, v45
	v_mul_f32_e32 v9, v34, v46
	v_mul_f32_e32 v13, v35, v47
	v_mul_f32_e32 v2, v176, v168
	v_mul_f32_e32 v6, v177, v169
	v_mul_f32_e32 v10, v178, v170
	v_mul_f32_e32 v14, v179, v171
	v_mul_f32_e32 v3, v180, v172
	v_mul_f32_e32 v7, v181, v173
	v_mul_f32_e32 v11, v182, v174
	v_mul_f32_e32 v15, v183, v175
	s_cmp_eq_u32 s1, 0
	s_cbranch_scc1 .Lfs_q
	s_lshl_b32 s0, s1, 1
	s_lshl_b32 s14, s1, 6
	v_mov_b32_e32 v18, v16
	v_add_u32_e32 v19, s14, v49
	ds_read_u16 v36, v18
	ds_read_b128 v[40:43], v19
	ds_read_u16 v37, v18 offset:272
	ds_read_b128 v[44:47], v19 offset:272
	ds_read_u16 v166, v18 offset:544
	ds_read_b128 v[168:171], v19 offset:544
	ds_read_u16 v167, v18 offset:816
	ds_read_b128 v[172:175], v19 offset:816

; __device__ __forceinline__ void prep_unit(const int PREP_STEPS, LAS unsigned char* lds, int uidx, bf16* Qg, bf16* Kg, bf16* Vg, bf16* KT, bf16* QK, const bf16* HALO, const float* wconv, const float* BETA, const float* GG, float* GC) {
;     ...
; #pragma unroll
;             for (int q = 0; q < 15; ++q) {
;                 const float xu = au[q], xw = aw[q];
;                 const int av = __builtin_bit_cast(int, Af[(16 * I + q) * 68 + 16 * I + l16]);
;                 Rows16<0>::run(av, xu, xw, au, aw, q);
;             }
.Lfs_q:
	ds_read_b32 v27, v198 offset:1904
	ds_read_b32 v28, v198 offset:2176
	ds_read_b32 v29, v198 offset:2448
	ds_read_b32 v30, v198 offset:2720
	ds_read_b32 v31, v198 offset:2992
	ds_read_b32 v32, v198 offset:3264
	ds_read_b32 v33, v198 offset:3536
	ds_read_b32 v34, v198 offset:3808
	s_waitcnt lgkmcnt(14)
	v_fmac_f32_dpp v4, v20, v0 row_newbcast:1 row_mask:0xf bank_mask:0xf bound_ctrl:1
	v_fmac_f32_dpp v8, v20, v0 row_newbcast:2 row_mask:0xf bank_mask:0xf bound_ctrl:1
	v_fmac_f32_dpp v12, v20, v0 row_newbcast:3 row_mask:0xf bank_mask:0xf bound_ctrl:1
	v_fmac_f32_dpp v1, v20, v0 row_newbcast:4 row_mask:0xf bank_mask:0xf bound_ctrl:1
	v_fmac_f32_dpp v5, v20, v0 row_newbcast:5 row_mask:0xf bank_mask:0xf bound_ctrl:1
	v_fmac_f32_dpp v9, v20, v0 row_newbcast:6 row_mask:0xf bank_mask:0xf bound_ctrl:1
	v_fmac_f32_dpp v13, v20, v0 row_newbcast:7 row_mask:0xf bank_mask:0xf bound_ctrl:1
	v_fmac_f32_dpp v2, v20, v0 row_newbcast:8 row_mask:0xf bank_mask:0xf bound_ctrl:1
	v_fmac_f32_dpp v6, v20, v0 row_newbcast:9 row_mask:0xf bank_mask:0xf bound_ctrl:1
	v_fmac_f32_dpp v10, v20, v0 row_newbcast:10 row_mask:0xf bank_mask:0xf bound_ctrl:1
	v_fmac_f32_dpp v14, v20, v0 row_newbcast:11 row_mask:0xf bank_mask:0xf bound_ctrl:1
	v_fmac_f32_dpp v3, v20, v0 row_newbcast:12 row_mask:0xf bank_mask:0xf bound_ctrl:1
	v_fmac_f32_dpp v7, v20, v0 row_newbcast:13 row_mask:0xf bank_mask:0xf bound_ctrl:1
	v_fmac_f32_dpp v11, v20, v0 row_newbcast:14 row_mask:0xf bank_mask:0xf bound_ctrl:1
	v_fmac_f32_dpp v15, v20, v0 row_newbcast:15 row_mask:0xf bank_mask:0xf bound_ctrl:1
	s_waitcnt lgkmcnt(13)
	v_fmac_f32_dpp v8, v21, v4 row_newbcast:2 row_mask:0xf bank_mask:0xf bound_ctrl:1
	v_fmac_f32_dpp v12, v21, v4 row_newbcast:3 row_mask:0xf bank_mask:0xf bound_ctrl:1
	v_fmac_f32_dpp v1, v21, v4 row_newbcast:4 row_mask:0xf bank_mask:0xf bound_ctrl:1
	v_fmac_f32_dpp v5, v21, v4 row_newbcast:5 row_mask:0xf bank_mask:0xf bound_ctrl:1
	v_fmac_f32_dpp v9, v21, v4 row_newbcast:6 row_mask:0xf bank_mask:0xf bound_ctrl:1
	v_fmac_f32_dpp v13, v21, v4 row_newbcast:7 row_mask:0xf bank_mask:0xf bound_ctrl:1
	v_fmac_f32_dpp v2, v21, v4 row_newbcast:8 row_mask:0xf bank_mask:0xf bound_ctrl:1
	v_fmac_f32_dpp v6, v21, v4 row_newbcast:9 row_mask:0xf bank_mask:0xf bound_ctrl:1
	v_fmac_f32_dpp v10, v21, v4 row_newbcast:10 row_mask:0xf bank_mask:0xf bound_ctrl:1
	v_fmac_f32_dpp v14, v21, v4 row_newbcast:11 row_mask:0xf bank_mask:0xf bound_ctrl:1
	v_fmac_f32_dpp v3, v21, v4 row_newbcast:12 row_mask:0xf bank_mask:0xf bound_ctrl:1
	v_fmac_f32_dpp v7, v21, v4 row_newbcast:13 row_mask:0xf bank_mask:0xf bound_ctrl:1
	v_fmac_f32_dpp v11, v21, v4 row_newbcast:14 row_mask:0xf bank_mask:0xf bound_ctrl:1
	v_fmac_f32_dpp v15, v21, v4 row_newbcast:15 row_mask:0xf bank_mask:0xf bound_ctrl:1
	s_waitcnt lgkmcnt(12)
	v_fmac_f32_dpp v12, v22, v8 row_newbcast:3 row_mask:0xf bank_mask:0xf bound_ctrl:1
	v_fmac_f32_dpp v1, v22, v8 row_newbcast:4 row_mask:0xf bank_mask:0xf bound_ctrl:1
	v_fmac_f32_dpp v5, v22, v8 row_newbcast:5 row_mask:0xf bank_mask:0xf bound_ctrl:1
	v_fmac_f32_dpp v9, v22, v8 row_newbcast:6 row_mask:0xf bank_mask:0xf bound_ctrl:1
	v_fmac_f32_dpp v13, v22, v8 row_newbcast:7 row_mask:0xf bank_mask:0xf bound_ctrl:1
	v_fmac_f32_dpp v2, v22, v8 row_newbcast:8 row_mask:0xf bank_mask:0xf bound_ctrl:1
	v_fmac_f32_dpp v6, v22, v8 row_newbcast:9 row_mask:0xf bank_mask:0xf bound_ctrl:1
	v_fmac_f32_dpp v10, v22, v8 row_newbcast:10 row_mask:0xf bank_mask:0xf bound_ctrl:1
	v_fmac_f32_dpp v14, v22, v8 row_newbcast:11 row_mask:0xf bank_mask:0xf bound_ctrl:1
	v_fmac_f32_dpp v3, v22, v8 row_newbcast:12 row_mask:0xf bank_mask:0xf bound_ctrl:1
	v_fmac_f32_dpp v7, v22, v8 row_newbcast:13 row_mask:0xf bank_mask:0xf bound_ctrl:1
	v_fmac_f32_dpp v11, v22, v8 row_newbcast:14 row_mask:0xf bank_mask:0xf bound_ctrl:1
	v_fmac_f32_dpp v15, v22, v8 row_newbcast:15 row_mask:0xf bank_mask:0xf bound_ctrl:1
	s_waitcnt lgkmcnt(11)
	v_fmac_f32_dpp v1, v23, v12 row_newbcast:4 row_mask:0xf bank_mask:0xf bound_ctrl:1
	v_fmac_f32_dpp v5, v23, v12 row_newbcast:5 row_mask:0xf bank_mask:0xf bound_ctrl:1
	v_fmac_f32_dpp v9, v23, v12 row_newbcast:6 row_mask:0xf bank_mask:0xf bound_ctrl:1
	v_fmac_f32_dpp v13, v23, v12 row_newbcast:7 row_mask:0xf bank_mask:0xf bound_ctrl:1
	v_fmac_f32_dpp v2, v23, v12 row_newbcast:8 row_mask:0xf bank_mask:0xf bound_ctrl:1
	v_fmac_f32_dpp v6, v23, v12 row_newbcast:9 row_mask:0xf bank_mask:0xf bound_ctrl:1
	v_fmac_f32_dpp v10, v23, v12 row_newbcast:10 row_mask:0xf bank_mask:0xf bound_ctrl:1
	v_fmac_f32_dpp v14, v23, v12 row_newbcast:11 row_mask:0xf bank_mask:0xf bound_ctrl:1
	v_fmac_f32_dpp v3, v23, v12 row_newbcast:12 row_mask:0xf bank_mask:0xf bound_ctrl:1
	v_fmac_f32_dpp v7, v23, v12 row_newbcast:13 row_mask:0xf bank_mask:0xf bound_ctrl:1
	v_fmac_f32_dpp v11, v23, v12 row_newbcast:14 row_mask:0xf bank_mask:0xf bound_ctrl:1
	v_fmac_f32_dpp v15, v23, v12 row_newbcast:15 row_mask:0xf bank_mask:0xf bound_ctrl:1
	s_waitcnt lgkmcnt(10)
	v_fmac_f32_dpp v5, v24, v1 row_newbcast:5 row_mask:0xf bank_mask:0xf bound_ctrl:1
	v_fmac_f32_dpp v9, v24, v1 row_newbcast:6 row_mask:0xf bank_mask:0xf bound_ctrl:1
	v_fmac_f32_dpp v13, v24, v1 row_newbcast:7 row_mask:0xf bank_mask:0xf bound_ctrl:1
	v_fmac_f32_dpp v2, v24, v1 row_newbcast:8 row_mask:0xf bank_mask:0xf bound_ctrl:1
	v_fmac_f32_dpp v6, v24, v1 row_newbcast:9 row_mask:0xf bank_mask:0xf bound_ctrl:1
	v_fmac_f32_dpp v10, v24, v1 row_newbcast:10 row_mask:0xf bank_mask:0xf bound_ctrl:1
	v_fmac_f32_dpp v14, v24, v1 row_newbcast:11 row_mask:0xf bank_mask:0xf bound_ctrl:1
	v_fmac_f32_dpp v3, v24, v1 row_newbcast:12 row_mask:0xf bank_mask:0xf bound_ctrl:1
	v_fmac_f32_dpp v7, v24, v1 row_newbcast:13 row_mask:0xf bank_mask:0xf bound_ctrl:1
	v_fmac_f32_dpp v11, v24, v1 row_newbcast:14 row_mask:0xf bank_mask:0xf bound_ctrl:1
	v_fmac_f32_dpp v15, v24, v1 row_newbcast:15 row_mask:0xf bank_mask:0xf bound_ctrl:1
	s_waitcnt lgkmcnt(9)
; __device__ __forceinline__ unsigned short f2bf(float f) { return (unsigned short)(cvt_pk_bf16(f, 0.f) & 0xffffu); }
; __device__ __forceinline__ void prep_unit(const int PREP_STEPS, LAS unsigned char* lds, int uidx, bf16* Qg, bf16* Kg, bf16* Vg, bf16* KT, bf16* QK, const bf16* HALO, const float* wconv, const float* BETA, const float* GG, float* GC) {
;     ...
;             for (int q = 0; q < 15; ++q) {
;                 const float xu = au[q], xw = aw[q];
;                 const int av = __builtin_bit_cast(int, Af[(16 * I + q) * 68 + 16 * I + l16]);
;                 Rows16<0>::run(av, xu, xw, au, aw, q);
;             }
; #pragma unroll
;             for (int r = 0; r < 16; ++r) { const unsigned short ub = f2bf(au[r]), wb = f2bf(aw[r]); Vs[(16 * I + r) * 136 + c] = ub; Ks[(16 * I + r) * 136 + c] = wb;
;                 dstu[(size_t)(16 * I + r) * D] = ub; dstw[(size_t)(16 * I + r) * D] = wb; }
	v_fmac_f32_dpp v9, v25, v5 row_newbcast:6 row_mask:0xf bank_mask:0xf bound_ctrl:1
	v_fmac_f32_dpp v13, v25, v5 row_newbcast:7 row_mask:0xf bank_mask:0xf bound_ctrl:1
	v_fmac_f32_dpp v2, v25, v5 row_newbcast:8 row_mask:0xf bank_mask:0xf bound_ctrl:1
	v_fmac_f32_dpp v6, v25, v5 row_newbcast:9 row_mask:0xf bank_mask:0xf bound_ctrl:1
	v_fmac_f32_dpp v10, v25, v5 row_newbcast:10 row_mask:0xf bank_mask:0xf bound_ctrl:1
	v_fmac_f32_dpp v14, v25, v5 row_newbcast:11 row_mask:0xf bank_mask:0xf bound_ctrl:1
	v_fmac_f32_dpp v3, v25, v5 row_newbcast:12 row_mask:0xf bank_mask:0xf bound_ctrl:1
	v_fmac_f32_dpp v7, v25, v5 row_newbcast:13 row_mask:0xf bank_mask:0xf bound_ctrl:1
	v_fmac_f32_dpp v11, v25, v5 row_newbcast:14 row_mask:0xf bank_mask:0xf bound_ctrl:1
	v_fmac_f32_dpp v15, v25, v5 row_newbcast:15 row_mask:0xf bank_mask:0xf bound_ctrl:1
	s_waitcnt lgkmcnt(8)
	v_fmac_f32_dpp v13, v26, v9 row_newbcast:7 row_mask:0xf bank_mask:0xf bound_ctrl:1
	v_fmac_f32_dpp v2, v26, v9 row_newbcast:8 row_mask:0xf bank_mask:0xf bound_ctrl:1
	v_fmac_f32_dpp v6, v26, v9 row_newbcast:9 row_mask:0xf bank_mask:0xf bound_ctrl:1
	v_fmac_f32_dpp v10, v26, v9 row_newbcast:10 row_mask:0xf bank_mask:0xf bound_ctrl:1
	v_fmac_f32_dpp v14, v26, v9 row_newbcast:11 row_mask:0xf bank_mask:0xf bound_ctrl:1
	v_fmac_f32_dpp v3, v26, v9 row_newbcast:12 row_mask:0xf bank_mask:0xf bound_ctrl:1
	v_fmac_f32_dpp v7, v26, v9 row_newbcast:13 row_mask:0xf bank_mask:0xf bound_ctrl:1
	v_fmac_f32_dpp v11, v26, v9 row_newbcast:14 row_mask:0xf bank_mask:0xf bound_ctrl:1
	v_fmac_f32_dpp v15, v26, v9 row_newbcast:15 row_mask:0xf bank_mask:0xf bound_ctrl:1
	s_waitcnt lgkmcnt(7)
	v_fmac_f32_dpp v2, v27, v13 row_newbcast:8 row_mask:0xf bank_mask:0xf bound_ctrl:1
	v_fmac_f32_dpp v6, v27, v13 row_newbcast:9 row_mask:0xf bank_mask:0xf bound_ctrl:1
	v_fmac_f32_dpp v10, v27, v13 row_newbcast:10 row_mask:0xf bank_mask:0xf bound_ctrl:1
	v_fmac_f32_dpp v14, v27, v13 row_newbcast:11 row_mask:0xf bank_mask:0xf bound_ctrl:1
	v_fmac_f32_dpp v3, v27, v13 row_newbcast:12 row_mask:0xf bank_mask:0xf bound_ctrl:1
	v_fmac_f32_dpp v7, v27, v13 row_newbcast:13 row_mask:0xf bank_mask:0xf bound_ctrl:1
	v_fmac_f32_dpp v11, v27, v13 row_newbcast:14 row_mask:0xf bank_mask:0xf bound_ctrl:1
	v_fmac_f32_dpp v15, v27, v13 row_newbcast:15 row_mask:0xf bank_mask:0xf bound_ctrl:1
	s_waitcnt lgkmcnt(6)
	v_fmac_f32_dpp v6, v28, v2 row_newbcast:9 row_mask:0xf bank_mask:0xf bound_ctrl:1
	v_fmac_f32_dpp v10, v28, v2 row_newbcast:10 row_mask:0xf bank_mask:0xf bound_ctrl:1
	v_fmac_f32_dpp v14, v28, v2 row_newbcast:11 row_mask:0xf bank_mask:0xf bound_ctrl:1
	v_fmac_f32_dpp v3, v28, v2 row_newbcast:12 row_mask:0xf bank_mask:0xf bound_ctrl:1
	v_fmac_f32_dpp v7, v28, v2 row_newbcast:13 row_mask:0xf bank_mask:0xf bound_ctrl:1
	v_fmac_f32_dpp v11, v28, v2 row_newbcast:14 row_mask:0xf bank_mask:0xf bound_ctrl:1
	v_fmac_f32_dpp v15, v28, v2 row_newbcast:15 row_mask:0xf bank_mask:0xf bound_ctrl:1
	s_waitcnt lgkmcnt(5)
	v_fmac_f32_dpp v10, v29, v6 row_newbcast:10 row_mask:0xf bank_mask:0xf bound_ctrl:1
	v_fmac_f32_dpp v14, v29, v6 row_newbcast:11 row_mask:0xf bank_mask:0xf bound_ctrl:1
	v_fmac_f32_dpp v3, v29, v6 row_newbcast:12 row_mask:0xf bank_mask:0xf bound_ctrl:1
	v_fmac_f32_dpp v7, v29, v6 row_newbcast:13 row_mask:0xf bank_mask:0xf bound_ctrl:1
	v_fmac_f32_dpp v11, v29, v6 row_newbcast:14 row_mask:0xf bank_mask:0xf bound_ctrl:1
	v_fmac_f32_dpp v15, v29, v6 row_newbcast:15 row_mask:0xf bank_mask:0xf bound_ctrl:1
	s_waitcnt lgkmcnt(4)
	v_fmac_f32_dpp v14, v30, v10 row_newbcast:11 row_mask:0xf bank_mask:0xf bound_ctrl:1
	v_fmac_f32_dpp v3, v30, v10 row_newbcast:12 row_mask:0xf bank_mask:0xf bound_ctrl:1
	v_fmac_f32_dpp v7, v30, v10 row_newbcast:13 row_mask:0xf bank_mask:0xf bound_ctrl:1
	v_fmac_f32_dpp v11, v30, v10 row_newbcast:14 row_mask:0xf bank_mask:0xf bound_ctrl:1
	v_fmac_f32_dpp v15, v30, v10 row_newbcast:15 row_mask:0xf bank_mask:0xf bound_ctrl:1
	s_waitcnt lgkmcnt(3)
	v_fmac_f32_dpp v3, v31, v14 row_newbcast:12 row_mask:0xf bank_mask:0xf bound_ctrl:1
	v_fmac_f32_dpp v7, v31, v14 row_newbcast:13 row_mask:0xf bank_mask:0xf bound_ctrl:1
	v_fmac_f32_dpp v11, v31, v14 row_newbcast:14 row_mask:0xf bank_mask:0xf bound_ctrl:1
	v_fmac_f32_dpp v15, v31, v14 row_newbcast:15 row_mask:0xf bank_mask:0xf bound_ctrl:1
	s_waitcnt lgkmcnt(2)
	v_fmac_f32_dpp v7, v32, v3 row_newbcast:13 row_mask:0xf bank_mask:0xf bound_ctrl:1
	v_fmac_f32_dpp v11, v32, v3 row_newbcast:14 row_mask:0xf bank_mask:0xf bound_ctrl:1
	v_fmac_f32_dpp v15, v32, v3 row_newbcast:15 row_mask:0xf bank_mask:0xf bound_ctrl:1
	s_waitcnt lgkmcnt(1)
	v_fmac_f32_dpp v11, v33, v7 row_newbcast:14 row_mask:0xf bank_mask:0xf bound_ctrl:1
	v_fmac_f32_dpp v15, v33, v7 row_newbcast:15 row_mask:0xf bank_mask:0xf bound_ctrl:1
	s_waitcnt lgkmcnt(0)
	s_nop 1
	v_fmac_f32_dpp v15, v34, v11 row_newbcast:15 row_mask:0xf bank_mask:0xf bound_ctrl:1
	v_cvt_pk_bf16_f32 v20, v0, v0
	v_cvt_pk_bf16_f32 v21, v4, v4
	v_cvt_pk_bf16_f32 v22, v8, v8
	v_cvt_pk_bf16_f32 v23, v12, v12
	v_cvt_pk_bf16_f32 v24, v1, v1
	v_cvt_pk_bf16_f32 v25, v5, v5
	v_cvt_pk_bf16_f32 v26, v9, v9
	v_cvt_pk_bf16_f32 v27, v13, v13
	v_cvt_pk_bf16_f32 v28, v2, v2
	v_cvt_pk_bf16_f32 v29, v6, v6
	v_cvt_pk_bf16_f32 v30, v10, v10
	v_cvt_pk_bf16_f32 v31, v14, v14
	v_cvt_pk_bf16_f32 v32, v3, v3
	v_cvt_pk_bf16_f32 v33, v7, v7
	v_cvt_pk_bf16_f32 v34, v11, v11
	v_cvt_pk_bf16_f32 v35, v15, v15
	ds_write_b16 v17, v20
	ds_write_b16 v17, v21 offset:272
	ds_write_b16 v17, v22 offset:544
	ds_write_b16 v17, v23 offset:816
	ds_write_b16 v17, v24 offset:1088
	ds_write_b16 v17, v25 offset:1360
	ds_write_b16 v17, v26 offset:1632
	ds_write_b16 v17, v27 offset:1904
	ds_write_b16 v17, v28 offset:2176
	ds_write_b16 v17, v29 offset:2448
	ds_write_b16 v17, v30 offset:2720
	ds_write_b16 v17, v31 offset:2992
	ds_write_b16 v17, v32 offset:3264
	ds_write_b16 v17, v33 offset:3536
	ds_write_b16 v17, v34 offset:3808
	ds_write_b16 v17, v35 offset:4080
	v_add_u32_e32 v17, 0x1100, v17
	v_add_u32_e32 v48, 64, v48
	s_add_i32 s1, s1, 1
	s_cmp_lg_u32 s1, 4
	s_cbranch_scc1 .Lfs_I
	s_branch .LBB0_637
